# softmax max tree as 4 independent chains
# speedup vs baseline: 1.0445x; 1.0044x over previous
; DI void diff_core(unsigned char* smem, const u16* qptr, const u16* kbase, const u16* vtbase, int vld,
;                   int ntb, int ntw, int nvalid, int ks0, const float* lut, int qpos, bool active, bool grpB,
;                   f32x16 (&O)[4], float& l_out) {
;     ...
;     float mx = S[0][0];
; #pragma unroll
;     for (int kb = 0; kb < 2; ++kb)
; #pragma unroll
;       for (int i = 0; i < 16; ++i) mx = fmaxf(mx, S[kb][i]);
;     {
;       const unsigned um = __float_as_uint(mx);
;       const auto sw = __builtin_amdgcn_permlane32_swap(um, um, false, false);
;       mx = fmaxf(__uint_as_float(sw[0]), __uint_as_float(sw[1]));
;     }
;     if (t == 0) {
;       m = mx;
; #pragma unroll
;       for (int kb = 0; kb < 2; ++kb)
; #pragma unroll
;         for (int i = 0; i < 16; ++i) S[kb][i] -= mx;
;     } else if (__any(mx > 8.f)) {
;       const float d = fmaxf(mx, 0.f);
;       const float alpha = __builtin_amdgcn_exp2f(-d);
;       m += d;
;       l *= alpha;
; #pragma unroll
;       for (int tt = 0; tt < 4; ++tt)
; #pragma unroll
;         for (int e = 0; e < 16; ++e) O[tt][e] *= alpha;
; #pragma unroll
;       for (int kb = 0; kb < 2; ++kb)
; #pragma unroll
;         for (int i = 0; i < 16; ++i) S[kb][i] -= d;
;     }
.LBB0_367:
	v_max3_f32 v144, v96, v97, v98
	v_max3_f32 v145, v104, v105, v106
	v_max3_f32 v146, v112, v113, v114
	v_max3_f32 v147, v120, v121, v122
	v_max3_f32 v144, v144, v99, v100
	v_max3_f32 v145, v145, v107, v108
	v_max3_f32 v146, v146, v115, v116
	v_max3_f32 v147, v147, v123, v124
	v_max3_f32 v144, v144, v101, v102
	v_max3_f32 v145, v145, v109, v110
	v_max3_f32 v146, v146, v117, v118
	v_max3_f32 v147, v147, v125, v126
	v_max_f32_e32 v144, v144, v103
	v_max_f32_e32 v145, v145, v111
	v_max_f32_e32 v146, v146, v119
	v_max_f32_e32 v147, v147, v127
	v_max3_f32 v144, v144, v145, v146
	v_max_f32_e32 v144, v144, v147
	v_mov_b32_e32 v145, v144
	s_nop 1
	v_permlane32_swap_b32_e32 v144, v145
	v_max_f32_e32 v144, v144, v145
	v_cmp_lt_f32_e32 vcc, s23, v144
	s_cbranch_vccz .LBB0_358
	v_max_f32_e32 v144, v144, v144
	v_max_f32_e32 v144, 0, v144
	v_exp_f32_e64 v146, -v144
	v_add_f32_e32 v191, v191, v144
	v_xor_b32_e32 v232, 0x80000000, v191
	v_mov_b32_e32 v233, v232
	v_mov_b32_e32 v234, v232
	v_mov_b32_e32 v235, v232
	v_mov_b32_e32 v236, v232
	v_mov_b32_e32 v237, v232
	v_mov_b32_e32 v238, v232
	v_mov_b32_e32 v239, v232
	v_mov_b32_e32 v240, v232
	v_mov_b32_e32 v241, v232
	v_mov_b32_e32 v242, v232
	v_mov_b32_e32 v243, v232
	v_mov_b32_e32 v244, v232
	v_mov_b32_e32 v245, v232
	v_mov_b32_e32 v246, v232
	v_mov_b32_e32 v247, v232
	v_pk_add_f32 v[96:97], v[96:97], v[144:145] op_sel_hi:[1,0] neg_lo:[0,1] neg_hi:[0,1]
	v_pk_add_f32 v[98:99], v[98:99], v[144:145] op_sel_hi:[1,0] neg_lo:[0,1] neg_hi:[0,1]
	v_pk_mul_f32 v[14:15], v[14:15], v[146:147] op_sel_hi:[1,0]
	v_pk_mul_f32 v[12:13], v[12:13], v[146:147] op_sel_hi:[1,0]
	v_pk_mul_f32 v[10:11], v[10:11], v[146:147] op_sel_hi:[1,0]
	v_pk_mul_f32 v[8:9], v[8:9], v[146:147] op_sel_hi:[1,0]
	v_pk_mul_f32 v[6:7], v[6:7], v[146:147] op_sel_hi:[1,0]
	v_pk_mul_f32 v[4:5], v[4:5], v[146:147] op_sel_hi:[1,0]
	v_pk_mul_f32 v[2:3], v[2:3], v[146:147] op_sel_hi:[1,0]
	v_pk_mul_f32 v[0:1], v[0:1], v[146:147] op_sel_hi:[1,0]
	v_pk_mul_f32 v[30:31], v[30:31], v[146:147] op_sel_hi:[1,0]
	v_pk_mul_f32 v[28:29], v[28:29], v[146:147] op_sel_hi:[1,0]
	v_pk_mul_f32 v[26:27], v[26:27], v[146:147] op_sel_hi:[1,0]
	v_pk_mul_f32 v[24:25], v[24:25], v[146:147] op_sel_hi:[1,0]
	v_pk_mul_f32 v[22:23], v[22:23], v[146:147] op_sel_hi:[1,0]
	v_pk_mul_f32 v[20:21], v[20:21], v[146:147] op_sel_hi:[1,0]
	v_pk_mul_f32 v[18:19], v[18:19], v[146:147] op_sel_hi:[1,0]
	v_pk_mul_f32 v[16:17], v[16:17], v[146:147] op_sel_hi:[1,0]
	v_pk_mul_f32 v[46:47], v[46:47], v[146:147] op_sel_hi:[1,0]
	v_pk_mul_f32 v[44:45], v[44:45], v[146:147] op_sel_hi:[1,0]
	v_pk_mul_f32 v[42:43], v[42:43], v[146:147] op_sel_hi:[1,0]
	v_pk_mul_f32 v[40:41], v[40:41], v[146:147] op_sel_hi:[1,0]
	v_pk_mul_f32 v[38:39], v[38:39], v[146:147] op_sel_hi:[1,0]
	v_pk_mul_f32 v[36:37], v[36:37], v[146:147] op_sel_hi:[1,0]
	v_pk_mul_f32 v[34:35], v[34:35], v[146:147] op_sel_hi:[1,0]
	v_pk_mul_f32 v[32:33], v[32:33], v[146:147] op_sel_hi:[1,0]
	v_pk_mul_f32 v[62:63], v[62:63], v[146:147] op_sel_hi:[1,0]
	v_pk_mul_f32 v[60:61], v[60:61], v[146:147] op_sel_hi:[1,0]
	v_pk_mul_f32 v[58:59], v[58:59], v[146:147] op_sel_hi:[1,0]
	v_pk_mul_f32 v[56:57], v[56:57], v[146:147] op_sel_hi:[1,0]
	v_pk_mul_f32 v[54:55], v[54:55], v[146:147] op_sel_hi:[1,0]
	v_pk_mul_f32 v[52:53], v[52:53], v[146:147] op_sel_hi:[1,0]
	v_pk_mul_f32 v[50:51], v[50:51], v[146:147] op_sel_hi:[1,0]
	v_pk_mul_f32 v[48:49], v[48:49], v[146:147] op_sel_hi:[1,0]
	v_mul_f32_e32 v181, v181, v146
	v_pk_add_f32 v[100:101], v[100:101], v[144:145] op_sel_hi:[1,0] neg_lo:[0,1] neg_hi:[0,1]
	v_pk_add_f32 v[102:103], v[102:103], v[144:145] op_sel_hi:[1,0] neg_lo:[0,1] neg_hi:[0,1]
	v_pk_add_f32 v[104:105], v[104:105], v[144:145] op_sel_hi:[1,0] neg_lo:[0,1] neg_hi:[0,1]
	v_pk_add_f32 v[106:107], v[106:107], v[144:145] op_sel_hi:[1,0] neg_lo:[0,1] neg_hi:[0,1]
	v_pk_add_f32 v[108:109], v[108:109], v[144:145] op_sel_hi:[1,0] neg_lo:[0,1] neg_hi:[0,1]
	v_pk_add_f32 v[110:111], v[110:111], v[144:145] op_sel_hi:[1,0] neg_lo:[0,1] neg_hi:[0,1]
	v_pk_add_f32 v[112:113], v[112:113], v[144:145] op_sel_hi:[1,0] neg_lo:[0,1] neg_hi:[0,1]
	v_pk_add_f32 v[114:115], v[114:115], v[144:145] op_sel_hi:[1,0] neg_lo:[0,1] neg_hi:[0,1]
	v_pk_add_f32 v[116:117], v[116:117], v[144:145] op_sel_hi:[1,0] neg_lo:[0,1] neg_hi:[0,1]
	v_pk_add_f32 v[118:119], v[118:119], v[144:145] op_sel_hi:[1,0] neg_lo:[0,1] neg_hi:[0,1]
	v_pk_add_f32 v[120:121], v[120:121], v[144:145] op_sel_hi:[1,0] neg_lo:[0,1] neg_hi:[0,1]
	v_pk_add_f32 v[122:123], v[122:123], v[144:145] op_sel_hi:[1,0] neg_lo:[0,1] neg_hi:[0,1]
	v_pk_add_f32 v[124:125], v[124:125], v[144:145] op_sel_hi:[1,0] neg_lo:[0,1] neg_hi:[0,1]
	v_pk_add_f32 v[126:127], v[126:127], v[144:145] op_sel_hi:[1,0] neg_lo:[0,1] neg_hi:[0,1]
	s_branch .LBB0_358

; DI void diff_core(unsigned char* smem, const u16* qptr, const u16* kbase, const u16* vtbase, int vld,
;                   int ntb, int ntw, int nvalid, int ks0, const float* lut, int qpos, bool active, bool grpB,
;                   f32x16 (&O)[4], float& l_out) {
;     ...
;     float mx = S[0][0];
; #pragma unroll
;     for (int kb = 0; kb < 2; ++kb)
; #pragma unroll
;       for (int i = 0; i < 16; ++i) mx = fmaxf(mx, S[kb][i]);
;     {
;       const unsigned um = __float_as_uint(mx);
;       const auto sw = __builtin_amdgcn_permlane32_swap(um, um, false, false);
;       mx = fmaxf(__uint_as_float(sw[0]), __uint_as_float(sw[1]));
;     }
;     if (t == 0) {
;       m = mx;
; #pragma unroll
;       for (int kb = 0; kb < 2; ++kb)
; #pragma unroll
;         for (int i = 0; i < 16; ++i) S[kb][i] -= mx;
;     } else if (__any(mx > 8.f)) {
;       const float d = fmaxf(mx, 0.f);
;       const float alpha = __builtin_amdgcn_exp2f(-d);
;       m += d;
;       l *= alpha;
; #pragma unroll
;       for (int tt = 0; tt < 4; ++tt)
; #pragma unroll
;         for (int e = 0; e < 16; ++e) O[tt][e] *= alpha;
; #pragma unroll
;       for (int kb = 0; kb < 2; ++kb)
; #pragma unroll
;         for (int i = 0; i < 16; ++i) S[kb][i] -= d;
;     }
.LBB0_381:
	v_max3_f32 v97, v80, v81, v82
	v_max3_f32 v98, v88, v89, v90
	v_max3_f32 v99, v64, v65, v66
	v_max3_f32 v100, v72, v73, v74
	v_max3_f32 v97, v97, v83, v84
	v_max3_f32 v98, v98, v91, v92
	v_max3_f32 v99, v99, v67, v68
	v_max3_f32 v100, v100, v75, v76
	v_max3_f32 v97, v97, v85, v86
	v_max3_f32 v98, v98, v93, v94
	v_max3_f32 v99, v99, v69, v70
	v_max3_f32 v100, v100, v77, v78
	v_max_f32_e32 v97, v97, v87
	v_max_f32_e32 v98, v98, v95
	v_max_f32_e32 v99, v99, v71
	v_max_f32_e32 v100, v100, v79
	v_max3_f32 v97, v97, v98, v99
	v_max_f32_e32 v97, v97, v100
	v_mov_b32_e32 v98, v97
	s_nop 1
	v_permlane32_swap_b32_e32 v97, v98
	v_max_f32_e32 v97, v97, v98
	v_cmp_lt_f32_e32 vcc, s23, v97
	s_cbranch_vccz .LBB0_383
	v_max_f32_e32 v97, v97, v97
	v_max_f32_e32 v98, 0, v97
	v_exp_f32_e64 v100, -v98
	v_add_f32_e32 v189, v189, v98
	v_xor_b32_e32 v232, 0x80000000, v189
	v_mov_b32_e32 v233, v232
	v_mov_b32_e32 v234, v232
	v_mov_b32_e32 v235, v232
	v_mov_b32_e32 v236, v232
	v_mov_b32_e32 v237, v232
	v_mov_b32_e32 v238, v232
	v_mov_b32_e32 v239, v232
	v_mov_b32_e32 v240, v232
	v_mov_b32_e32 v241, v232
	v_mov_b32_e32 v242, v232
	v_mov_b32_e32 v243, v232
	v_mov_b32_e32 v244, v232
	v_mov_b32_e32 v245, v232
	v_mov_b32_e32 v246, v232
	v_mov_b32_e32 v247, v232
	v_pk_add_f32 v[80:81], v[80:81], v[98:99] op_sel_hi:[1,0] neg_lo:[0,1] neg_hi:[0,1]
	v_pk_add_f32 v[82:83], v[82:83], v[98:99] op_sel_hi:[1,0] neg_lo:[0,1] neg_hi:[0,1]
	v_pk_mul_f32 v[14:15], v[14:15], v[100:101] op_sel_hi:[1,0]
	v_pk_mul_f32 v[12:13], v[12:13], v[100:101] op_sel_hi:[1,0]
	v_pk_mul_f32 v[10:11], v[10:11], v[100:101] op_sel_hi:[1,0]
	v_pk_mul_f32 v[8:9], v[8:9], v[100:101] op_sel_hi:[1,0]
	v_pk_mul_f32 v[6:7], v[6:7], v[100:101] op_sel_hi:[1,0]
	v_pk_mul_f32 v[4:5], v[4:5], v[100:101] op_sel_hi:[1,0]
	v_pk_mul_f32 v[2:3], v[2:3], v[100:101] op_sel_hi:[1,0]
	v_pk_mul_f32 v[0:1], v[0:1], v[100:101] op_sel_hi:[1,0]
	v_pk_mul_f32 v[30:31], v[30:31], v[100:101] op_sel_hi:[1,0]
	v_pk_mul_f32 v[28:29], v[28:29], v[100:101] op_sel_hi:[1,0]
	v_pk_mul_f32 v[26:27], v[26:27], v[100:101] op_sel_hi:[1,0]
	v_pk_mul_f32 v[24:25], v[24:25], v[100:101] op_sel_hi:[1,0]
	v_pk_mul_f32 v[22:23], v[22:23], v[100:101] op_sel_hi:[1,0]
	v_pk_mul_f32 v[20:21], v[20:21], v[100:101] op_sel_hi:[1,0]
	v_pk_mul_f32 v[18:19], v[18:19], v[100:101] op_sel_hi:[1,0]
	v_pk_mul_f32 v[16:17], v[16:17], v[100:101] op_sel_hi:[1,0]
	v_pk_mul_f32 v[46:47], v[46:47], v[100:101] op_sel_hi:[1,0]
	v_pk_mul_f32 v[44:45], v[44:45], v[100:101] op_sel_hi:[1,0]
	v_pk_mul_f32 v[42:43], v[42:43], v[100:101] op_sel_hi:[1,0]
	v_pk_mul_f32 v[40:41], v[40:41], v[100:101] op_sel_hi:[1,0]
	v_pk_mul_f32 v[38:39], v[38:39], v[100:101] op_sel_hi:[1,0]
	v_pk_mul_f32 v[36:37], v[36:37], v[100:101] op_sel_hi:[1,0]
	v_pk_mul_f32 v[34:35], v[34:35], v[100:101] op_sel_hi:[1,0]
	v_pk_mul_f32 v[32:33], v[32:33], v[100:101] op_sel_hi:[1,0]
	v_pk_mul_f32 v[62:63], v[62:63], v[100:101] op_sel_hi:[1,0]
	v_pk_mul_f32 v[60:61], v[60:61], v[100:101] op_sel_hi:[1,0]
	v_pk_mul_f32 v[58:59], v[58:59], v[100:101] op_sel_hi:[1,0]
	v_pk_mul_f32 v[56:57], v[56:57], v[100:101] op_sel_hi:[1,0]
	v_pk_mul_f32 v[54:55], v[54:55], v[100:101] op_sel_hi:[1,0]
	v_pk_mul_f32 v[52:53], v[52:53], v[100:101] op_sel_hi:[1,0]
	v_pk_mul_f32 v[50:51], v[50:51], v[100:101] op_sel_hi:[1,0]
	v_pk_mul_f32 v[48:49], v[48:49], v[100:101] op_sel_hi:[1,0]
	v_mul_f32_e32 v181, v181, v100
	v_pk_add_f32 v[84:85], v[84:85], v[98:99] op_sel_hi:[1,0] neg_lo:[0,1] neg_hi:[0,1]
	v_pk_add_f32 v[86:87], v[86:87], v[98:99] op_sel_hi:[1,0] neg_lo:[0,1] neg_hi:[0,1]
	v_pk_add_f32 v[88:89], v[88:89], v[98:99] op_sel_hi:[1,0] neg_lo:[0,1] neg_hi:[0,1]
	v_pk_add_f32 v[90:91], v[90:91], v[98:99] op_sel_hi:[1,0] neg_lo:[0,1] neg_hi:[0,1]
	v_pk_add_f32 v[92:93], v[92:93], v[98:99] op_sel_hi:[1,0] neg_lo:[0,1] neg_hi:[0,1]
	v_pk_add_f32 v[94:95], v[94:95], v[98:99] op_sel_hi:[1,0] neg_lo:[0,1] neg_hi:[0,1]
	v_pk_add_f32 v[64:65], v[64:65], v[98:99] op_sel_hi:[1,0] neg_lo:[0,1] neg_hi:[0,1]
	v_pk_add_f32 v[66:67], v[66:67], v[98:99] op_sel_hi:[1,0] neg_lo:[0,1] neg_hi:[0,1]
	v_pk_add_f32 v[68:69], v[68:69], v[98:99] op_sel_hi:[1,0] neg_lo:[0,1] neg_hi:[0,1]
	v_pk_add_f32 v[70:71], v[70:71], v[98:99] op_sel_hi:[1,0] neg_lo:[0,1] neg_hi:[0,1]
	v_pk_add_f32 v[72:73], v[72:73], v[98:99] op_sel_hi:[1,0] neg_lo:[0,1] neg_hi:[0,1]
	v_pk_add_f32 v[74:75], v[74:75], v[98:99] op_sel_hi:[1,0] neg_lo:[0,1] neg_hi:[0,1]
	v_pk_add_f32 v[76:77], v[76:77], v[98:99] op_sel_hi:[1,0] neg_lo:[0,1] neg_hi:[0,1]
	v_pk_add_f32 v[78:79], v[78:79], v[98:99] op_sel_hi:[1,0] neg_lo:[0,1] neg_hi:[0,1]
